# v54: grid barrier XCD leader releases its XCD before issuing its own acquire invalidate
# speedup vs baseline: 1.0076x; 1.0019x over previous
.LBB0_142:
	s_or_b64 exec, exec, s[6:7]
	s_mov_b64 s[6:7], exec
	v_mbcnt_lo_u32_b32 v1, s6, 0
	v_mbcnt_hi_u32_b32 v1, s7, v1
	v_cmp_eq_u32_e32 vcc, 0, v1
	s_waitcnt vmcnt(0)
	s_and_saveexec_b64 s[8:9], vcc
	s_cbranch_execz .LBB0_144
	s_bcnt1_i32_b64 s6, s[6:7]
	v_mov_b32_e32 v1, 0x2000
	v_mov_b32_e32 v2, s6
	global_atomic_add v1, v2, s[4:5] offset:1024
.LBB0_144:
	s_or_b64 exec, exec, s[8:9]
	buffer_inv sc1
	s_waitcnt vmcnt(0)

.LBB0_625:
	s_or_b64 exec, exec, s[4:5]
	s_mov_b64 s[4:5], exec
	v_mbcnt_lo_u32_b32 v1, s4, 0
	v_mbcnt_hi_u32_b32 v1, s5, v1
	v_cmp_eq_u32_e32 vcc, 0, v1
	s_waitcnt vmcnt(0)
	s_and_saveexec_b64 s[6:7], vcc
	s_cbranch_execz .LBB0_627
	s_bcnt1_i32_b64 s4, s[4:5]
	v_mov_b32_e32 v1, 0x2000
	v_mov_b32_e32 v2, s4
	global_atomic_add v1, v2, s[2:3] offset:1024
.LBB0_627:
	s_or_b64 exec, exec, s[6:7]
	buffer_inv sc1
	s_waitcnt vmcnt(0)

.LBB0_1602:
	s_or_b64 exec, exec, s[6:7]
	s_mov_b64 s[6:7], exec
	v_mbcnt_lo_u32_b32 v1, s6, 0
	v_mbcnt_hi_u32_b32 v1, s7, v1
	v_cmp_eq_u32_e32 vcc, 0, v1
	s_waitcnt vmcnt(0)
	s_and_saveexec_b64 s[8:9], vcc
	s_cbranch_execz .LBB0_1604
	s_bcnt1_i32_b64 s6, s[6:7]
	v_mov_b32_e32 v1, 0x2000
	v_mov_b32_e32 v2, s6
	global_atomic_add v1, v2, s[2:3] offset:1024
